# diff-attn and dilated epilogues: weight loads hoisted with counted waits, 8-byte row stores widened to 16-byte via permlane32_swap
# speedup vs baseline: 1.0056x; 1.0040x over previous
.LBB0_343:
	s_andn2_b64 vcc, exec, s[10:11]
	s_waitcnt lgkmcnt(0)
	s_barrier
	s_cbranch_vccnz .LBB0_290
	global_load_dwordx4 v[112:115], v65, s[0:1]
	global_load_dwordx4 v[116:119], v65, s[0:1] offset:32
	global_load_dwordx4 v[120:123], v65, s[0:1] offset:64
	global_load_dwordx4 v[124:127], v65, s[0:1] offset:96
	global_load_dwordx4 v[128:131], v65, s[0:1] offset:128
	global_load_dwordx4 v[132:135], v65, s[0:1] offset:160
	global_load_dwordx4 v[136:139], v65, s[0:1] offset:192
	global_load_dwordx4 v[140:143], v65, s[0:1] offset:224
	global_load_dwordx4 v[192:195], v65, s[0:1] offset:256
	global_load_dwordx4 v[196:199], v65, s[0:1] offset:288
	global_load_dwordx4 v[200:203], v65, s[0:1] offset:320
	global_load_dwordx4 v[204:207], v65, s[0:1] offset:352
	global_load_dwordx4 v[220:223], v65, s[0:1] offset:384
	global_load_dwordx4 v[224:227], v65, s[0:1] offset:416
	global_load_dwordx4 v[228:231], v65, s[0:1] offset:448
	global_load_dwordx4 v[232:235], v65, s[0:1] offset:480
	ds_read_b128 v[66:69], v79
	ds_read_b128 v[70:73], v79 offset:32
	s_lshl_b32 s90, s2, 1
	v_lshlrev_b32_e32 v168, 2, v157
	ds_read_b128 v[82:85], v79 offset:256
	s_waitcnt lgkmcnt(2)
	v_fma_f32 v66, v48, v64, -v66
	v_fma_f32 v48, v49, v64, -v67
	v_fma_f32 v49, v50, v64, -v68
	v_fma_f32 v51, v51, v64, -v69
	s_waitcnt lgkmcnt(1)
	v_fma_f32 v67, v52, v64, -v70
	v_fma_f32 v53, v53, v64, -v71
	ds_read_b128 v[68:71], v79 offset:64
	v_mul_f32_e32 v80, v48, v48
	v_fmac_f32_e32 v80, v66, v66
	v_fma_f32 v54, v54, v64, -v72
	v_fma_f32 v55, v55, v64, -v73
	s_waitcnt lgkmcnt(0)
	v_fma_f32 v52, v58, v64, -v70
	v_fma_f32 v50, v59, v64, -v71
	ds_read_b128 v[70:73], v79 offset:96
	v_fmac_f32_e32 v80, v49, v49
	v_fmac_f32_e32 v80, v51, v51
	v_fmac_f32_e32 v80, v67, v67
	v_fmac_f32_e32 v80, v53, v53
	v_fmac_f32_e32 v80, v54, v54
	v_fma_f32 v68, v56, v64, -v68
	v_fma_f32 v56, v57, v64, -v69
	s_waitcnt lgkmcnt(0)
	v_fma_f32 v69, v60, v64, -v70
	v_fma_f32 v61, v61, v64, -v71
	v_fma_f32 v60, v62, v64, -v72
	v_fma_f32 v59, v63, v64, -v73
	ds_read_b128 v[70:73], v79 offset:128
	v_fmac_f32_e32 v80, v55, v55
	v_fmac_f32_e32 v80, v68, v68
	v_fmac_f32_e32 v80, v56, v56
	v_fmac_f32_e32 v80, v52, v52
	v_fmac_f32_e32 v80, v50, v50
	s_waitcnt lgkmcnt(0)
	v_fma_f32 v58, v32, v64, -v70
	v_fma_f32 v57, v33, v64, -v71
	v_fma_f32 v33, v34, v64, -v72
	v_fma_f32 v32, v35, v64, -v73
	ds_read_b128 v[72:75], v79 offset:160
	v_fmac_f32_e32 v80, v69, v69
	v_fmac_f32_e32 v80, v61, v61
	v_fmac_f32_e32 v80, v60, v60
	v_fmac_f32_e32 v80, v59, v59
	v_fmac_f32_e32 v80, v58, v58
	s_waitcnt lgkmcnt(0)
	v_fma_f32 v71, v36, v64, -v72
	v_fma_f32 v70, v37, v64, -v73
	v_fma_f32 v63, v38, v64, -v74
	v_fma_f32 v62, v39, v64, -v75
	ds_read_b128 v[72:75], v79 offset:192
	v_fmac_f32_e32 v80, v57, v57
	v_fmac_f32_e32 v80, v33, v33
	v_fmac_f32_e32 v80, v32, v32
	v_fmac_f32_e32 v80, v71, v71
	v_fmac_f32_e32 v80, v70, v70
	s_waitcnt lgkmcnt(0)
	v_fma_f32 v39, v40, v64, -v72
	v_fma_f32 v37, v41, v64, -v73
	v_fma_f32 v36, v42, v64, -v74
	v_fma_f32 v35, v43, v64, -v75
	ds_read_b128 v[40:43], v79 offset:224
	v_fmac_f32_e32 v80, v63, v63
	v_fmac_f32_e32 v80, v62, v62
	v_fmac_f32_e32 v80, v39, v39
	v_fmac_f32_e32 v80, v37, v37
	v_fmac_f32_e32 v80, v36, v36
	s_waitcnt lgkmcnt(0)
	v_fma_f32 v73, v45, v64, -v41
	v_fma_f32 v47, v47, v64, -v43
	v_fma_f32 v45, v16, v64, -v82
	v_fma_f32 v43, v17, v64, -v83
	v_fma_f32 v41, v18, v64, -v84
	v_fma_f32 v38, v19, v64, -v85
	ds_read_b128 v[16:19], v79 offset:288
	v_fmac_f32_e32 v80, v35, v35
	v_fma_f32 v74, v44, v64, -v40
	v_fmac_f32_e32 v80, v74, v74
	v_fmac_f32_e32 v80, v73, v73
	v_fma_f32 v72, v46, v64, -v42
	v_fmac_f32_e32 v80, v72, v72
	v_fmac_f32_e32 v80, v47, v47
	s_waitcnt lgkmcnt(0)
	v_fma_f32 v78, v20, v64, -v16
	v_fma_f32 v77, v21, v64, -v17
	v_fma_f32 v76, v22, v64, -v18
	v_fma_f32 v75, v23, v64, -v19
	ds_read_b128 v[16:19], v79 offset:320
	v_fmac_f32_e32 v80, v45, v45
	v_fmac_f32_e32 v80, v43, v43
	v_fmac_f32_e32 v80, v41, v41
	v_fmac_f32_e32 v80, v38, v38
	v_fmac_f32_e32 v80, v78, v78
	s_waitcnt lgkmcnt(0)
	v_fma_f32 v46, v24, v64, -v16
	v_fma_f32 v44, v25, v64, -v17
	v_fma_f32 v42, v26, v64, -v18
	v_fma_f32 v40, v27, v64, -v19
	ds_read_b128 v[16:19], v79 offset:352
	v_fmac_f32_e32 v80, v77, v77
	v_fmac_f32_e32 v80, v76, v76
	v_fmac_f32_e32 v80, v75, v75
	v_fmac_f32_e32 v80, v46, v46
	v_fmac_f32_e32 v80, v44, v44
	s_waitcnt lgkmcnt(0)
	v_fma_f32 v34, v28, v64, -v16
	v_fma_f32 v28, v29, v64, -v17
	v_fma_f32 v27, v30, v64, -v18
	v_fma_f32 v26, v31, v64, -v19
	ds_read_b128 v[16:19], v79 offset:384
	v_fmac_f32_e32 v80, v42, v42
	v_fmac_f32_e32 v80, v40, v40
	v_fmac_f32_e32 v80, v34, v34
	v_fmac_f32_e32 v80, v28, v28
	v_fmac_f32_e32 v80, v27, v27
	s_waitcnt lgkmcnt(0)
	v_fma_f32 v25, v0, v64, -v16
	v_fma_f32 v24, v1, v64, -v17
	v_fma_f32 v23, v2, v64, -v18
	v_fma_f32 v22, v3, v64, -v19
	ds_read_b128 v[0:3], v79 offset:416
	v_fmac_f32_e32 v80, v26, v26
	v_fmac_f32_e32 v80, v25, v25
	v_fmac_f32_e32 v80, v24, v24
	v_fmac_f32_e32 v80, v23, v23
	v_fmac_f32_e32 v80, v22, v22
	s_waitcnt lgkmcnt(0)
	v_fma_f32 v21, v4, v64, -v0
	v_fmac_f32_e32 v80, v21, v21
	v_fma_f32 v20, v5, v64, -v1
	v_pk_fma_f32 v[18:19], v[6:7], v[64:65], v[2:3] op_sel_hi:[1,0,1] neg_lo:[0,0,1] neg_hi:[0,0,1]
	v_fmac_f32_e32 v80, v20, v20
	v_pk_mul_f32 v[0:1], v[18:19], v[18:19]
	s_nop 0
	v_add_f32_e32 v0, v0, v80
	v_add_f32_e32 v4, v1, v0
	ds_read_b128 v[0:3], v79 offset:448
	s_waitcnt lgkmcnt(0)
	v_pk_fma_f32 v[16:17], v[8:9], v[64:65], v[0:1] op_sel_hi:[1,0,1] neg_lo:[0,0,1] neg_hi:[0,0,1]
	s_nop 0
	v_pk_mul_f32 v[0:1], v[16:17], v[16:17]
	v_pk_fma_f32 v[8:9], v[10:11], v[64:65], v[2:3] op_sel_hi:[1,0,1] neg_lo:[0,0,1] neg_hi:[0,0,1]
	v_add_f32_e32 v0, v0, v4
	v_add_f32_e32 v4, v1, v0
	v_pk_mul_f32 v[0:1], v[8:9], v[8:9]
	s_nop 0
	v_add_f32_e32 v0, v0, v4
	v_add_f32_e32 v4, v1, v0
	ds_read_b128 v[0:3], v79 offset:480
	s_waitcnt lgkmcnt(0)
	v_pk_fma_f32 v[6:7], v[12:13], v[64:65], v[0:1] op_sel_hi:[1,0,1] neg_lo:[0,0,1] neg_hi:[0,0,1]
	s_nop 0
	v_pk_mul_f32 v[0:1], v[6:7], v[6:7]
	s_nop 0
	v_add_f32_e32 v0, v0, v4
	v_pk_fma_f32 v[4:5], v[14:15], v[64:65], v[2:3] op_sel_hi:[1,0,1] neg_lo:[0,0,1] neg_hi:[0,0,1]
	v_add_f32_e32 v10, v1, v0
	v_pk_mul_f32 v[0:1], v[4:5], v[4:5]
	s_nop 0
	v_add_f32_e32 v0, v0, v10
	v_add_f32_e32 v0, v1, v0
	ds_bpermute_b32 v1, v161, v0
	s_waitcnt lgkmcnt(0)
	v_add_f32_e32 v0, v0, v1
	v_fmamk_f32 v0, v0, 0x3c000000, v172
	v_cmp_gt_f32_e32 vcc, s52, v0
	v_mul_f32_e32 v1, 0x4b800000, v0
	s_nop 0
	v_cndmask_b32_e32 v0, v0, v1, vcc
	v_rsq_f32_e32 v0, v0
	s_nop 0
	v_mul_f32_e32 v1, 0x45800000, v0
	v_cndmask_b32_e32 v0, v0, v1, vcc
	v_mul_f32_e32 v12, v145, v0
	v_lshlrev_b64 v[0:1], 11, v[146:147]
	v_lshl_add_u64 v[0:1], s[46:47], 0, v[0:1]
	v_lshl_add_u64 v[10:11], v[0:1], 0, s[90:91]
	v_mul_f32_e32 v13, v66, v12
	s_waitcnt vmcnt(15)
	v_mul_f32_e32 v0, v112, v13
	v_mul_f32_e32 v13, v48, v12
	v_mul_f32_e32 v1, v113, v13
	v_cvt_pk_bf16_f32 v236, v0, v1
	v_mul_f32_e32 v0, v49, v12
	v_mul_f32_e32 v1, v51, v12
	v_mul_f32_e32 v0, v114, v0
	v_mul_f32_e32 v1, v115, v1
	v_cvt_pk_bf16_f32 v237, v0, v1
	v_lshl_add_u64 v[0:1], v[10:11], 0, v[168:169]
	v_mul_f32_e32 v2, v67, v12
	v_mul_f32_e32 v3, v53, v12
	v_mul_f32_e32 v10, v55, v12
	s_waitcnt vmcnt(14)
	v_mul_f32_e32 v2, v116, v2
	v_mul_f32_e32 v3, v117, v3
	v_cvt_pk_bf16_f32 v238, v2, v3
	v_mul_f32_e32 v3, v54, v12
	v_mul_f32_e32 v3, v118, v3
	v_mul_f32_e32 v10, v119, v10
	v_cvt_pk_bf16_f32 v239, v3, v10
	s_nop 1
	v_permlane32_swap_b32_e32 v236, v238
	v_permlane32_swap_b32_e32 v237, v239
	global_store_dwordx4 v[0:1], v[236:239], off
	v_mul_f32_e32 v2, v68, v12
	v_mul_f32_e32 v3, v56, v12
	v_mul_f32_e32 v10, v50, v12
	s_waitcnt vmcnt(14)
	v_mul_f32_e32 v2, v120, v2
	v_mul_f32_e32 v3, v121, v3
	v_cvt_pk_bf16_f32 v240, v2, v3
	v_mul_f32_e32 v3, v52, v12
	v_mul_f32_e32 v3, v122, v3
	v_mul_f32_e32 v10, v123, v10
	v_cvt_pk_bf16_f32 v241, v3, v10
	v_mul_f32_e32 v2, v69, v12
	v_mul_f32_e32 v3, v61, v12
	v_mul_f32_e32 v10, v59, v12
	s_waitcnt vmcnt(13)
	v_mul_f32_e32 v2, v124, v2
	v_mul_f32_e32 v3, v125, v3
	v_cvt_pk_bf16_f32 v242, v2, v3
	v_mul_f32_e32 v3, v60, v12
	v_mul_f32_e32 v3, v126, v3
	v_mul_f32_e32 v10, v127, v10
	v_cvt_pk_bf16_f32 v243, v3, v10
	s_nop 1
	v_permlane32_swap_b32_e32 v240, v242
	v_permlane32_swap_b32_e32 v241, v243
	global_store_dwordx4 v[0:1], v[240:243], off offset:32
	v_mul_f32_e32 v2, v58, v12
	v_mul_f32_e32 v3, v57, v12
	v_mul_f32_e32 v10, v32, v12
	s_waitcnt vmcnt(13)
	v_mul_f32_e32 v2, v128, v2
	v_mul_f32_e32 v3, v129, v3
	v_cvt_pk_bf16_f32 v244, v2, v3
	v_mul_f32_e32 v3, v33, v12
	v_mul_f32_e32 v3, v130, v3
	v_mul_f32_e32 v10, v131, v10
	v_cvt_pk_bf16_f32 v245, v3, v10
	v_mul_f32_e32 v2, v71, v12
	v_mul_f32_e32 v3, v70, v12
	v_mul_f32_e32 v10, v62, v12
	s_waitcnt vmcnt(12)
	v_mul_f32_e32 v2, v132, v2
	v_mul_f32_e32 v3, v133, v3
	v_cvt_pk_bf16_f32 v246, v2, v3
	v_mul_f32_e32 v3, v63, v12
	v_mul_f32_e32 v3, v134, v3
	v_mul_f32_e32 v10, v135, v10
	v_cvt_pk_bf16_f32 v247, v3, v10
	s_nop 1
	v_permlane32_swap_b32_e32 v244, v246
	v_permlane32_swap_b32_e32 v245, v247
	global_store_dwordx4 v[0:1], v[244:247], off offset:64
	v_mul_f32_e32 v2, v39, v12
	v_mul_f32_e32 v3, v37, v12
	v_mul_f32_e32 v10, v35, v12
	s_waitcnt vmcnt(12)
	v_mul_f32_e32 v2, v136, v2
	v_mul_f32_e32 v3, v137, v3
	v_cvt_pk_bf16_f32 v248, v2, v3
	v_mul_f32_e32 v3, v36, v12
	v_mul_f32_e32 v3, v138, v3
	v_mul_f32_e32 v10, v139, v10
	v_cvt_pk_bf16_f32 v249, v3, v10
	v_mul_f32_e32 v2, v74, v12
	v_mul_f32_e32 v3, v73, v12
	v_mul_f32_e32 v10, v47, v12
	s_waitcnt vmcnt(11)
	v_mul_f32_e32 v2, v140, v2
	v_mul_f32_e32 v3, v141, v3
	v_cvt_pk_bf16_f32 v250, v2, v3
	v_mul_f32_e32 v3, v72, v12
	v_mul_f32_e32 v3, v142, v3
	v_mul_f32_e32 v10, v143, v10
	v_cvt_pk_bf16_f32 v251, v3, v10
	s_nop 1
	v_permlane32_swap_b32_e32 v248, v250
	v_permlane32_swap_b32_e32 v249, v251
	global_store_dwordx4 v[0:1], v[248:251], off offset:96
	v_mul_f32_e32 v2, v45, v12
	v_mul_f32_e32 v3, v43, v12
	v_mul_f32_e32 v10, v38, v12
	s_waitcnt vmcnt(11)
	v_mul_f32_e32 v2, v192, v2
	v_mul_f32_e32 v3, v193, v3
	v_cvt_pk_bf16_f32 v236, v2, v3
	v_mul_f32_e32 v3, v41, v12
	v_mul_f32_e32 v3, v194, v3
	v_mul_f32_e32 v10, v195, v10
	v_cvt_pk_bf16_f32 v237, v3, v10
	v_mul_f32_e32 v2, v78, v12
	v_mul_f32_e32 v3, v77, v12
	v_mul_f32_e32 v10, v75, v12
	s_waitcnt vmcnt(10)
	v_mul_f32_e32 v2, v196, v2
	v_mul_f32_e32 v3, v197, v3
	v_cvt_pk_bf16_f32 v238, v2, v3
	v_mul_f32_e32 v3, v76, v12
	v_mul_f32_e32 v3, v198, v3
	v_mul_f32_e32 v10, v199, v10
	v_cvt_pk_bf16_f32 v239, v3, v10
	s_nop 1
	v_permlane32_swap_b32_e32 v236, v238
	v_permlane32_swap_b32_e32 v237, v239
	global_store_dwordx4 v[0:1], v[236:239], off offset:128
	v_mul_f32_e32 v2, v46, v12
	v_mul_f32_e32 v3, v44, v12
	v_mul_f32_e32 v10, v40, v12
	s_waitcnt vmcnt(10)
	v_mul_f32_e32 v2, v200, v2
	v_mul_f32_e32 v3, v201, v3
	v_cvt_pk_bf16_f32 v240, v2, v3
	v_mul_f32_e32 v3, v42, v12
	v_mul_f32_e32 v3, v202, v3
	v_mul_f32_e32 v10, v203, v10
	v_cvt_pk_bf16_f32 v241, v3, v10
	v_mul_f32_e32 v2, v34, v12
	v_mul_f32_e32 v3, v28, v12
	v_mul_f32_e32 v10, v26, v12
	s_waitcnt vmcnt(9)
	v_mul_f32_e32 v2, v204, v2
	v_mul_f32_e32 v3, v205, v3
	v_cvt_pk_bf16_f32 v242, v2, v3
	v_mul_f32_e32 v3, v27, v12
	v_mul_f32_e32 v3, v206, v3
	v_mul_f32_e32 v10, v207, v10
	v_cvt_pk_bf16_f32 v243, v3, v10
	s_nop 1
	v_permlane32_swap_b32_e32 v240, v242
	v_permlane32_swap_b32_e32 v241, v243
	global_store_dwordx4 v[0:1], v[240:243], off offset:160
	v_mul_f32_e32 v2, v25, v12
	v_mul_f32_e32 v3, v24, v12
	v_mul_f32_e32 v10, v22, v12
	s_waitcnt vmcnt(9)
	v_mul_f32_e32 v2, v220, v2
	v_mul_f32_e32 v3, v221, v3
	v_cvt_pk_bf16_f32 v244, v2, v3
	v_mul_f32_e32 v3, v23, v12
	v_mul_f32_e32 v3, v222, v3
	v_mul_f32_e32 v10, v223, v10
	v_cvt_pk_bf16_f32 v245, v3, v10
	v_mul_f32_e32 v2, v21, v12
	v_mul_f32_e32 v3, v20, v12
	v_mul_f32_e32 v10, v19, v12
	s_waitcnt vmcnt(8)
	v_mul_f32_e32 v2, v224, v2
	v_mul_f32_e32 v3, v225, v3
	v_cvt_pk_bf16_f32 v246, v2, v3
	v_mul_f32_e32 v3, v18, v12
	v_mul_f32_e32 v3, v226, v3
	v_mul_f32_e32 v10, v227, v10
	v_cvt_pk_bf16_f32 v247, v3, v10
	s_nop 1
	v_permlane32_swap_b32_e32 v244, v246
	v_permlane32_swap_b32_e32 v245, v247
	global_store_dwordx4 v[0:1], v[244:247], off offset:192
	v_mul_f32_e32 v2, v16, v12
	v_mul_f32_e32 v3, v17, v12
	s_waitcnt vmcnt(8)
	v_mul_f32_e32 v2, v228, v2
	v_mul_f32_e32 v3, v229, v3
	v_cvt_pk_bf16_f32 v248, v2, v3
	v_mul_f32_e32 v3, v8, v12
	v_mul_f32_e32 v3, v230, v3
	v_mul_f32_e32 v8, v9, v12
	v_mul_f32_e32 v8, v231, v8
	v_cvt_pk_bf16_f32 v249, v3, v8
	v_mul_f32_e32 v2, v6, v12
	v_mul_f32_e32 v3, v7, v12
	s_waitcnt vmcnt(7)
	v_mul_f32_e32 v2, v2, v232
	v_mul_f32_e32 v3, v3, v233
	v_cvt_pk_bf16_f32 v250, v2, v3
	v_mul_f32_e32 v3, v4, v12
	v_mul_f32_e32 v3, v3, v234
	v_mul_f32_e32 v4, v5, v12
	v_mul_f32_e32 v4, v4, v235
	v_cvt_pk_bf16_f32 v251, v3, v4
	s_nop 1
	v_permlane32_swap_b32_e32 v248, v250
	v_permlane32_swap_b32_e32 v249, v251
	global_store_dwordx4 v[0:1], v[248:251], off offset:224
	s_branch .LBB0_290

.LBB0_644:
	s_cmp_ge_i32 s35, s36
	s_cbranch_scc1 .LBB0_668
	s_ashr_i32 s54, s18, 8
	s_and_b32 s0, s35, 31
	s_and_b32 s1, s35, 0xfffffc00
	s_cmpk_eq_i32 s1, 0x400
	s_cselect_b32 s1, 2, 4
	s_cmpk_gt_u32 s35, 0x3ff
	s_cselect_b32 s16, s1, 0
	s_lshr_b32 s1, 32, s16
	s_sub_i32 s2, 5, s16
	s_add_i32 s1, s1, -1
	s_lshr_b32 s17, s0, s2
	s_and_b32 s0, s1, s0
	s_lshl_b32 s55, s35, 5
	s_lshl_b32 s2, s0, 8
	s_and_b32 s90, s55, 0x6000
	s_cmp_eq_u32 s0, 0
	v_ashrrev_i32_e32 v134, 3, v0
	s_movk_i32 s20, 0x80
	s_cselect_b64 s[0:1], -1, 0
	s_add_i32 s19, s2, 0xffffff80
	v_cmp_gt_i32_e64 s[2:3], s20, v134
	v_lshlrev_b32_e32 v1, 3, v0
	v_add_u32_e32 v135, 0x80, v134
	s_and_b64 vcc, s[2:3], s[0:1]
	v_and_b32_e32 v2, 56, v1
	v_cndmask_b32_e32 v1, v134, v135, vcc
	v_add_u32_e32 v1, s19, v1
	v_lshlrev_b32_e32 v1, s16, v1
	v_add_u32_e32 v4, s17, v1
	v_ashrrev_i32_e32 v5, 31, v4
	v_lshl_add_u64 v[4:5], v[4:5], 0, s[90:91]
	v_mov_b64_e32 v[6:7], s[48:49]
	v_mad_u64_u32 v[8:9], s[4:5], v4, s29, v[6:7]
	v_add_u32_e32 v1, 0x200, v0
	s_lshl_b32 s4, s35, 2
	v_ashrrev_i32_e32 v136, 3, v1
	s_and_b32 s14, s4, 0x380
	v_cmp_gt_i32_e64 s[4:5], s20, v136
	v_add_u32_e32 v137, 0x80, v136
	s_and_b64 vcc, s[4:5], s[0:1]
	v_mad_i32_i24 v9, v5, s29, v9
	s_mov_b32 s15, s91
	v_cndmask_b32_e32 v1, v136, v137, vcc
	v_lshl_add_u64 v[4:5], v[8:9], 0, s[14:15]
	v_lshlrev_b32_e32 v168, 1, v2
	v_add_u32_e32 v1, s19, v1
	v_lshl_add_u64 v[4:5], v[4:5], 0, v[168:169]
	v_lshlrev_b32_e32 v1, s16, v1
	global_load_dwordx4 v[64:67], v[4:5], off offset:1024
	global_load_dwordx4 v[68:71], v[4:5], off offset:2048
	v_add_u32_e32 v4, s17, v1
	v_ashrrev_i32_e32 v5, 31, v4
	v_lshl_add_u64 v[4:5], v[4:5], 0, s[90:91]
	v_add_u32_e32 v1, 0x400, v0
	v_mad_u64_u32 v[8:9], s[6:7], v4, s29, v[6:7]
	v_ashrrev_i32_e32 v138, 3, v1
	v_cmp_gt_i32_e64 s[6:7], s20, v138
	v_add_u32_e32 v139, 0x80, v138
	s_and_b64 vcc, s[6:7], s[0:1]
	v_mad_i32_i24 v9, v5, s29, v9
	v_cndmask_b32_e32 v1, v138, v139, vcc
	v_lshl_add_u64 v[4:5], v[8:9], 0, s[14:15]
	v_add_u32_e32 v1, s19, v1
	v_lshl_add_u64 v[4:5], v[4:5], 0, v[168:169]
	v_lshlrev_b32_e32 v1, s16, v1
	global_load_dwordx4 v[72:75], v[4:5], off offset:1024
	global_load_dwordx4 v[76:79], v[4:5], off offset:2048
	v_add_u32_e32 v4, s17, v1
	v_ashrrev_i32_e32 v5, 31, v4
	v_lshl_add_u64 v[4:5], v[4:5], 0, s[90:91]
	v_add_u32_e32 v1, 0x600, v0
	v_mad_u64_u32 v[8:9], s[8:9], v4, s29, v[6:7]
	v_ashrrev_i32_e32 v140, 3, v1
	v_cmp_gt_i32_e64 s[8:9], s20, v140
	v_add_u32_e32 v141, 0x80, v140
	s_and_b64 vcc, s[8:9], s[0:1]
	v_mad_i32_i24 v9, v5, s29, v9
	v_cndmask_b32_e32 v1, v140, v141, vcc
	v_lshl_add_u64 v[4:5], v[8:9], 0, s[14:15]
	v_add_u32_e32 v1, s19, v1
	v_lshl_add_u64 v[4:5], v[4:5], 0, v[168:169]
	v_lshlrev_b32_e32 v1, s16, v1
	global_load_dwordx4 v[80:83], v[4:5], off offset:1024
	global_load_dwordx4 v[84:87], v[4:5], off offset:2048
	v_add_u32_e32 v4, s17, v1
	v_ashrrev_i32_e32 v5, 31, v4
	v_lshl_add_u64 v[4:5], v[4:5], 0, s[90:91]
	v_add_u32_e32 v1, 0x800, v0
	v_mad_u64_u32 v[8:9], s[10:11], v4, s29, v[6:7]
	v_ashrrev_i32_e32 v142, 3, v1
	v_cmp_gt_i32_e64 s[10:11], s20, v142
	v_add_u32_e32 v143, 0x80, v142
	s_and_b64 vcc, s[10:11], s[0:1]
	v_mad_i32_i24 v9, v5, s29, v9
	v_cndmask_b32_e32 v1, v142, v143, vcc
	v_lshl_add_u64 v[4:5], v[8:9], 0, s[14:15]
	v_add_u32_e32 v1, s19, v1
	v_lshl_add_u64 v[4:5], v[4:5], 0, v[168:169]
	v_lshlrev_b32_e32 v1, s16, v1
	global_load_dwordx4 v[88:91], v[4:5], off offset:1024
	global_load_dwordx4 v[92:95], v[4:5], off offset:2048
	v_add_u32_e32 v4, s17, v1
	v_ashrrev_i32_e32 v5, 31, v4
	v_lshl_add_u64 v[4:5], v[4:5], 0, s[90:91]
	v_add_u32_e32 v1, 0xa00, v0
	v_mad_u64_u32 v[8:9], s[12:13], v4, s29, v[6:7]
	v_ashrrev_i32_e32 v144, 3, v1
	v_cmp_gt_i32_e64 s[12:13], s20, v144
	v_add_u32_e32 v145, 0x80, v144
	s_and_b64 vcc, s[12:13], s[0:1]
	v_mad_i32_i24 v9, v5, s29, v9
	v_cndmask_b32_e32 v1, v144, v145, vcc
	v_lshl_add_u64 v[4:5], v[8:9], 0, s[14:15]
	v_add_u32_e32 v1, s19, v1
	v_lshl_add_u64 v[4:5], v[4:5], 0, v[168:169]
	v_lshlrev_b32_e32 v1, s16, v1
	global_load_dwordx4 v[96:99], v[4:5], off offset:1024
	global_load_dwordx4 v[100:103], v[4:5], off offset:2048
	v_add_u32_e32 v4, s17, v1
	v_ashrrev_i32_e32 v5, 31, v4
	v_lshl_add_u64 v[4:5], v[4:5], 0, s[90:91]
	v_mad_u64_u32 v[6:7], s[0:1], v4, s29, v[6:7]
	v_mad_i32_i24 v7, v5, s29, v7
	v_lshl_add_u64 v[4:5], v[6:7], 0, s[14:15]
	v_lshl_add_u64 v[4:5], v[4:5], 0, v[168:169]
	global_load_dwordx4 v[104:107], v[4:5], off offset:1024
	global_load_dwordx4 v[108:111], v[4:5], off offset:2048
	s_movk_i32 s1, 0x100
	v_and_b32_e32 v11, 64, v213
	v_cmp_gt_i32_e64 s[14:15], s1, v0
	v_subrev_u32_e32 v146, 64, v0
	s_movk_i32 s1, 0x81
	v_xor_b32_e32 v10, 32, v213
	v_add_u32_e32 v11, 64, v11
	v_cmp_gt_u32_e64 s[16:17], s1, v146
	s_lshr_b32 s1, s18, 1
	v_cmp_lt_i32_e32 vcc, v10, v11
	v_bfe_u32 v3, v0, 5, 1
	s_and_b32 s1, s1, 0x60
	s_lshl_b32 s18, s54, 7
	v_cndmask_b32_e32 v10, v213, v10, vcc
	v_and_b32_e32 v1, 31, v0
	s_or_b32 s18, s18, s1
	v_lshlrev_b32_e32 v6, 2, v3
	v_lshlrev_b32_e32 v149, 2, v10
	v_bfe_u32 v10, v0, 2, 2
	v_lshlrev_b32_e32 v5, 2, v0
	v_readlane_b32 s19, v254, 59
	v_lshlrev_b32_e32 v4, 4, v0
	v_sub_u32_e32 v8, v1, v6
	v_or3_b32 v10, v10, v6, s18
	s_movk_i32 s20, 0xc0
	v_and_b32_e32 v0, 16, v0
	s_lshl_b32 s0, s35, 1
	v_lshl_add_u32 v8, v8, 2, s19
	v_mul_lo_u32 v10, v10, s20
	v_and_or_b32 v0, v5, 12, v0
	v_and_b32_e32 v4, 0x70, v4
	v_add_u32_e32 v148, 0x94, v8
	v_or_b32_e32 v8, s18, v1
	s_movk_i32 s21, 0x90
	v_add_u32_e32 v10, 0, v10
	v_lshlrev_b32_e32 v0, 1, v0
	s_mov_b32 s18, 0xd800
	s_cmpk_eq_i32 s1, 0x60
	v_add_u32_e32 v147, s19, v5
	v_add_u32_e32 v7, 0, v4
	v_lshlrev_b32_e32 v4, 3, v3
	v_mul_lo_u32 v8, v8, s21
	v_lshlrev_b32_e32 v9, 4, v3
	v_add3_u32 v150, v10, v0, s18
	v_cmp_eq_u32_e64 s[18:19], 0, v3
	v_mul_lo_u32 v0, v134, s21
	v_mul_lo_u32 v3, v134, s20
	v_mul_lo_u32 v5, v136, s21
	v_mul_lo_u32 v10, v136, s20
	v_mul_lo_u32 v11, v138, s21
	v_mul_lo_u32 v12, v138, s20
	v_mul_lo_u32 v13, v140, s21
	v_mul_lo_u32 v14, v140, s20
	v_mul_lo_u32 v15, v142, s21
	v_mul_lo_u32 v16, v142, s20
	v_mul_lo_u32 v17, v144, s21
	v_mul_lo_u32 v18, v144, s20
	s_cselect_b64 s[20:21], -1, 0
	s_cmp_lt_u32 s1, 64
	v_add_u32_e32 v8, 0, v8
	s_cselect_b64 s[22:23], -1, 0
	s_cmp_eq_u32 s1, 0
	s_cselect_b64 s[24:25], -1, 0
	v_or_b32_e32 v151, s1, v1
	s_add_i32 s56, s0, 2
	v_add_u32_e32 v152, v7, v0
	v_add_u32_e32 v153, v7, v3
	v_add_u32_e32 v154, v7, v5
	v_add_u32_e32 v155, v7, v10
	v_add_u32_e32 v156, v7, v11
	v_add_u32_e32 v157, v7, v12
	v_add_u32_e32 v158, v7, v13
	v_add_u32_e32 v159, v7, v14
	v_add_u32_e32 v160, v7, v15
	v_add_u32_e32 v161, v7, v16
	v_add_u32_e32 v162, v7, v17
	v_add_u32_e32 v163, v7, v18
	v_lshlrev_b32_e32 v128, 1, v4
	v_lshlrev_b32_e32 v130, 1, v2
	v_lshlrev_b32_e32 v168, 2, v6
	v_add_u32_e32 v164, v8, v9
	s_branch .LBB0_647

.LBB0_665:
	s_waitcnt lgkmcnt(0)
	v_add_f32_e32 v34, v34, v35
	v_div_scale_f32 v35, s[0:1], v34, v34, 1.0
	v_rcp_f32_e32 v36, v35
	s_lshl_b32 s0, s57, 6
	s_lshl_b32 s90, s0, 1
	v_lshl_add_u64 v[32:33], v[32:33], 0, s[90:91]
	v_fma_f32 v37, -v35, v36, 1.0
	v_fmac_f32_e32 v36, v37, v36
	v_div_scale_f32 v37, vcc, 1.0, v34, 1.0
	v_mul_f32_e32 v38, v37, v36
	v_fma_f32 v39, -v35, v38, v37
	v_fmac_f32_e32 v38, v39, v36
	v_fma_f32 v35, -v35, v38, v37
	v_div_fmas_f32 v35, v35, v36, v38
	v_div_fixup_f32 v35, v35, v34, 1.0
	v_mul_f32_e32 v16, v16, v35
	v_mul_f32_e32 v17, v17, v35
	v_cvt_pk_bf16_f32 v48, v16, v17
	v_mul_f32_e32 v17, v18, v35
	v_lshl_add_u64 v[32:33], v[32:33], 0, v[168:169]
	v_mul_f32_e32 v18, v19, v35
	v_cvt_pk_bf16_f32 v49, v17, v18
	v_mul_f32_e32 v16, v20, v35
	v_mul_f32_e32 v17, v21, v35
	v_cvt_pk_bf16_f32 v50, v16, v17
	v_mul_f32_e32 v17, v22, v35
	v_mul_f32_e32 v18, v23, v35
	v_cvt_pk_bf16_f32 v51, v17, v18
	s_nop 1
	v_permlane32_swap_b32_e32 v48, v50
	v_permlane32_swap_b32_e32 v49, v51
	global_store_dwordx4 v[32:33], v[48:51], off
	v_mul_f32_e32 v16, v24, v35
	v_mul_f32_e32 v17, v25, v35
	v_cvt_pk_bf16_f32 v52, v16, v17
	v_mul_f32_e32 v17, v26, v35
	v_mul_f32_e32 v18, v27, v35
	v_cvt_pk_bf16_f32 v53, v17, v18
	v_mul_f32_e32 v16, v28, v35
	v_mul_f32_e32 v17, v29, v35
	v_cvt_pk_bf16_f32 v54, v16, v17
	v_mul_f32_e32 v17, v30, v35
	v_mul_f32_e32 v0, v0, v35
	v_mul_f32_e32 v1, v1, v35
	v_mul_f32_e32 v18, v31, v35
	v_cvt_pk_bf16_f32 v55, v17, v18
	s_nop 1
	v_permlane32_swap_b32_e32 v52, v54
	v_permlane32_swap_b32_e32 v53, v55
	global_store_dwordx4 v[32:33], v[52:55], off offset:32
	v_cvt_pk_bf16_f32 v56, v0, v1
	v_mul_f32_e32 v1, v2, v35
	v_mul_f32_e32 v2, v3, v35
	v_cvt_pk_bf16_f32 v57, v1, v2
	v_mul_f32_e32 v0, v4, v35
	v_mul_f32_e32 v1, v5, v35
	v_cvt_pk_bf16_f32 v58, v0, v1
	v_mul_f32_e32 v1, v6, v35
	v_mul_f32_e32 v2, v7, v35
	v_cvt_pk_bf16_f32 v59, v1, v2
	s_nop 1
	v_permlane32_swap_b32_e32 v56, v58
	v_permlane32_swap_b32_e32 v57, v59
	global_store_dwordx4 v[32:33], v[56:59], off offset:64
	v_mul_f32_e32 v0, v8, v35
	v_mul_f32_e32 v1, v9, v35
	v_cvt_pk_bf16_f32 v60, v0, v1
	v_mul_f32_e32 v1, v10, v35
	v_mul_f32_e32 v2, v11, v35
	v_cvt_pk_bf16_f32 v61, v1, v2
	v_mul_f32_e32 v0, v12, v35
	v_mul_f32_e32 v1, v13, v35
	v_cvt_pk_bf16_f32 v62, v0, v1
	v_mul_f32_e32 v1, v14, v35
	v_mul_f32_e32 v2, v15, v35
	v_cvt_pk_bf16_f32 v63, v1, v2
	s_nop 1
	v_permlane32_swap_b32_e32 v60, v62
	v_permlane32_swap_b32_e32 v61, v63
	global_store_dwordx4 v[32:33], v[60:63], off offset:96
	s_and_saveexec_b64 s[0:1], s[18:19]
	s_cbranch_execz .LBB0_646
	v_log_f32_e32 v0, v34
	s_ashr_i32 s35, s34, 31
	s_lshl_b64 s[26:27], s[34:35], 20
	s_mov_b64 s[34:35], s[44:45]
	s_add_u32 s26, s34, s26
	v_add_f32_e32 v2, v112, v0
	s_addc_u32 s27, s35, s27
	v_lshlrev_b64 v[0:1], 5, v[132:133]
	v_lshl_add_u64 v[0:1], s[26:27], 0, v[0:1]
	s_lshl_b32 s90, s57, 2
	v_lshl_add_u64 v[0:1], v[0:1], 0, s[90:91]
	global_store_dword v[0:1], v2, off
	s_branch .LBB0_646
